# prep phase LoRA epilogue: bias loads hoisted out of the 16 serialized load-wait-store steps
# speedup vs baseline: 1.0168x; 1.0105x over previous
; DEV float sigmoid_f(float x) { return rcp_f(1.f + __expf(-x)); }
; template <int K, int NT, class Epi>
; DEV void small_gemm(const Params& p, const Ctx& cx, const char* As, int astride, const bf16_t* __restrict__ Bt, int n0, Epi epi) {
;     ...
;   for (int k0 = 0; k0 < K; k0 += 32) {
;     bf16x8 af[4];
; #pragma unroll
;     for (int i = 0; i < 4; ++i) af[i] = *(const bf16x8*)(As + (i * 16 + fr) * astride + (k0 + fq * 8) * 2);
; #pragma unroll
;     for (int jn = 0; jn < NT; ++jn) {
;       bf16x8 bf = *(const bf16x8*)(Bt + (size_t)(n0 + jn * 16 + fr) * K + k0 + fq * 8);
; #pragma unroll
;       for (int i = 0; i < 4; ++i) acc[i][jn] = __builtin_amdgcn_mfma_f32_16x16x32_f16(bf, af[i], acc[i][jn], 0, 0, 0);
;     }
;   }
; #pragma unroll
;   for (int i = 0; i < 4; ++i)
; #pragma unroll
;     for (int jn = 0; jn < NT; ++jn) epi(i * 16 + fr, n0 + jn * 16 + fq * 4, acc[i][jn]);
; DEV void prep_item(const Params& p, const Ctx& cx, int l, int item, char* smem) {
;     ...
;     for (int hf = 0; hf < 2; ++hf) small_gemm<64, 4>(p, cx, smem, 144, Bt, (tid >> 6) * 128 + hf * 64, [&](int m, int n, f32x4 v) {
;       float4 bbw = *(const float4*)(biasw + n), bba = *(const float4*)(biasa + n);
;       float4 bb = isA ? bba : bbw;
;       float r0 = sigmoid_f(v[0] + bb.x), r1 = sigmoid_f(v[1] + bb.y), r2 = sigmoid_f(v[2] + bb.z), r3 = sigmoid_f(v[3] + bb.w);
;       if (!isA) { r0 = __expf(-DECAY_SCALE * r0); r1 = __expf(-DECAY_SCALE * r1); r2 = __expf(-DECAY_SCALE * r2); r3 = __expf(-DECAY_SCALE * r3); }
;       h16x4 o4 = {(h16)r0, (h16)r1, (h16)r2, (h16)r3};
;       *(h16x4*)(dst + (size_t)(row0 + m) * 1024 + n) = o4;
.LBB0_358:
	v_or_b32_e32 v119, s4, v116
	v_or_b32_e32 v72, v119, v117
	v_or_b32_e32 v60, 32, v72
	v_ashrrev_i32_e32 v61, 31, v60
	v_lshlrev_b64 v[60:61], 7, v[60:61]
	v_lshl_add_u64 v[86:87], v[96:97], 0, v[60:61]
	global_load_dwordx4 v[60:63], v[86:87], off
	v_ashrrev_i32_e32 v73, 31, v72
	v_lshlrev_b64 v[32:33], 7, v[72:73]
	v_lshl_add_u64 v[74:75], v[96:97], 0, v[32:33]
	global_load_dwordx4 v[32:35], v[74:75], off
	v_or_b32_e32 v48, 16, v72
	v_ashrrev_i32_e32 v49, 31, v48
	v_lshlrev_b64 v[48:49], 7, v[48:49]
	v_lshl_add_u64 v[84:85], v[96:97], 0, v[48:49]
	global_load_dwordx4 v[48:51], v[84:85], off
	s_and_b64 vcc, exec, s[40:41]
	s_waitcnt vmcnt(1) lgkmcnt(7)
	v_mfma_f32_16x16x32_f16 v[36:39], v[32:35], v[0:3], 0
	v_mfma_f32_16x16x32_f16 v[68:71], v[60:63], v[0:3], 0
	s_waitcnt lgkmcnt(6)
	v_mfma_f32_16x16x32_f16 v[80:83], v[60:63], v[4:7], 0
	s_waitcnt lgkmcnt(5)
	v_mfma_f32_16x16x32_f16 v[106:109], v[60:63], v[8:11], 0
	s_waitcnt lgkmcnt(4)
	v_mfma_f32_16x16x32_f16 v[120:123], v[60:63], v[12:15], 0
	v_or_b32_e32 v60, 48, v72
	v_ashrrev_i32_e32 v61, 31, v60
	v_lshlrev_b64 v[60:61], 7, v[60:61]
	v_lshl_add_u64 v[110:111], v[96:97], 0, v[60:61]
	global_load_dwordx4 v[60:63], v[110:111], off
	v_mfma_f32_16x16x32_f16 v[40:43], v[32:35], v[4:7], 0
	global_load_dwordx4 v[72:75], v[74:75], off offset:64
	v_mfma_f32_16x16x32_f16 v[44:47], v[32:35], v[8:11], 0
	v_mfma_f32_16x16x32_f16 v[32:35], v[32:35], v[12:15], 0
	s_waitcnt vmcnt(2)
	v_mfma_f32_16x16x32_f16 v[52:55], v[48:51], v[0:3], 0
	v_mfma_f32_16x16x32_f16 v[56:59], v[48:51], v[4:7], 0
	v_mfma_f32_16x16x32_f16 v[64:67], v[48:51], v[8:11], 0
	v_mfma_f32_16x16x32_f16 v[48:51], v[48:51], v[12:15], 0
	s_waitcnt vmcnt(1)
	v_mfma_f32_16x16x32_f16 v[124:127], v[60:63], v[0:3], 0
	v_mfma_f32_16x16x32_f16 v[132:135], v[60:63], v[4:7], 0
	v_mfma_f32_16x16x32_f16 v[136:139], v[60:63], v[8:11], 0
	v_mfma_f32_16x16x32_f16 v[140:143], v[60:63], v[12:15], 0
	s_waitcnt vmcnt(0) lgkmcnt(1)
	v_mfma_f32_16x16x32_f16 v[60:63], v[72:75], v[24:27], v[44:47]
	s_waitcnt lgkmcnt(0)
	v_mfma_f32_16x16x32_f16 v[44:47], v[72:75], v[28:31], v[32:35]
	s_nop 2
	global_load_dwordx4 v[32:35], v[84:85], off offset:64
	v_mfma_f32_16x16x32_f16 v[92:95], v[72:75], v[16:19], v[36:39]
	v_mfma_f32_16x16x32_f16 v[76:79], v[72:75], v[20:23], v[40:43]
	s_waitcnt vmcnt(0)
	v_mfma_f32_16x16x32_f16 v[88:91], v[32:35], v[16:19], v[52:55]
	v_mfma_f32_16x16x32_f16 v[72:75], v[32:35], v[20:23], v[56:59]
	v_mfma_f32_16x16x32_f16 v[56:59], v[32:35], v[24:27], v[64:67]
	v_mfma_f32_16x16x32_f16 v[40:43], v[32:35], v[28:31], v[48:51]
	global_load_dwordx4 v[32:35], v[86:87], off offset:64
	s_waitcnt vmcnt(0)
	v_mfma_f32_16x16x32_f16 v[84:87], v[32:35], v[16:19], v[68:71]
	v_mfma_f32_16x16x32_f16 v[68:71], v[32:35], v[20:23], v[80:83]
	v_mfma_f32_16x16x32_f16 v[52:55], v[32:35], v[24:27], v[106:109]
	v_mfma_f32_16x16x32_f16 v[36:39], v[32:35], v[28:31], v[120:123]
	global_load_dwordx4 v[32:35], v[110:111], off offset:64
	v_or_b32_e32 v110, v119, v118
	v_ashrrev_i32_e32 v111, 31, v110
	v_lshlrev_b64 v[108:109], 2, v[110:111]
	v_lshl_add_u64 v[106:107], s[0:1], 0, v[108:109]
	v_lshl_add_u64 v[108:109], s[84:85], 0, v[108:109]
	global_load_dwordx4 v[188:191], v[106:107], off
	global_load_dwordx4 v[204:207], v[108:109], off
	global_load_dwordx4 v[192:195], v[106:107], off offset:64
	global_load_dwordx4 v[208:211], v[108:109], off offset:64
	global_load_dwordx4 v[196:199], v[106:107], off offset:128
	global_load_dwordx4 v[212:215], v[108:109], off offset:128
	global_load_dwordx4 v[200:203], v[106:107], off offset:192
	global_load_dwordx4 v[216:219], v[108:109], off offset:192
	s_waitcnt vmcnt(8)
	v_mfma_f32_16x16x32_f16 v[80:83], v[32:35], v[16:19], v[124:127]
	s_waitcnt vmcnt(0)
	v_cndmask_b32_e64 v188, v204, v188, s[38:39]
	v_cndmask_b32_e64 v189, v205, v189, s[38:39]
	v_cndmask_b32_e64 v190, v206, v190, s[38:39]
	v_cndmask_b32_e64 v191, v207, v191, s[38:39]
	v_cndmask_b32_e64 v192, v208, v192, s[38:39]
	v_cndmask_b32_e64 v193, v209, v193, s[38:39]
	v_cndmask_b32_e64 v194, v210, v194, s[38:39]
	v_cndmask_b32_e64 v195, v211, v195, s[38:39]
	v_cndmask_b32_e64 v196, v212, v196, s[38:39]
	v_cndmask_b32_e64 v197, v213, v197, s[38:39]
	v_cndmask_b32_e64 v198, v214, v198, s[38:39]
	v_cndmask_b32_e64 v199, v215, v199, s[38:39]
	v_cndmask_b32_e64 v200, v216, v200, s[38:39]
	v_cndmask_b32_e64 v201, v217, v201, s[38:39]
	v_cndmask_b32_e64 v202, v218, v202, s[38:39]
	v_cndmask_b32_e64 v203, v219, v203, s[38:39]
	v_add_f32_e32 v92, v92, v188
	v_add_f32_e32 v93, v93, v189
	v_add_f32_e32 v94, v94, v190
	v_add_f32_e32 v95, v95, v191
	v_mul_f32_e32 v92, 0xbfb8aa3b, v92
	v_mul_f32_e32 v93, 0xbfb8aa3b, v93
	v_mul_f32_e32 v94, 0xbfb8aa3b, v94
	v_mul_f32_e32 v95, 0xbfb8aa3b, v95
	v_exp_f32_e32 v92, v92
	v_exp_f32_e32 v93, v93
	v_exp_f32_e32 v94, v94
	v_exp_f32_e32 v95, v95
	v_add_f32_e32 v92, 1.0, v92
	v_add_f32_e32 v93, 1.0, v93
	v_add_f32_e32 v94, 1.0, v94
	v_add_f32_e32 v95, 1.0, v95
	v_mfma_f32_16x16x32_f16 v[64:67], v[32:35], v[20:23], v[132:135]
	v_rcp_f32_e32 v92, v92
	v_rcp_f32_e32 v93, v93
	v_rcp_f32_e32 v94, v94
	v_mfma_f32_16x16x32_f16 v[48:51], v[32:35], v[24:27], v[136:139]
	v_rcp_f32_e32 v95, v95
	v_mfma_f32_16x16x32_f16 v[32:35], v[32:35], v[28:31], v[140:143]
	s_cbranch_vccnz .LBB0_360
	v_mul_f32_e32 v92, 0xbf1b459e, v92
	v_mul_f32_e32 v93, 0xbf1b459e, v93
	v_mul_f32_e32 v94, 0xbf1b459e, v94
	v_mul_f32_e32 v95, 0xbf1b459e, v95
	v_mul_f32_e32 v92, 0x3fb8aa3b, v92
	v_mul_f32_e32 v93, 0x3fb8aa3b, v93
	v_mul_f32_e32 v94, 0x3fb8aa3b, v94
	v_mul_f32_e32 v95, 0x3fb8aa3b, v95
	v_exp_f32_e32 v92, v92
	v_exp_f32_e32 v93, v93
	v_exp_f32_e32 v94, v94
	v_exp_f32_e32 v95, v95
; DEV float sigmoid_f(float x) { return rcp_f(1.f + __expf(-x)); }
; DEV void prep_item(const Params& p, const Ctx& cx, int l, int item, char* smem) {
;     ...
;     for (int hf = 0; hf < 2; ++hf) small_gemm<64, 4>(p, cx, smem, 144, Bt, (tid >> 6) * 128 + hf * 64, [&](int m, int n, f32x4 v) {
;       float4 bbw = *(const float4*)(biasw + n), bba = *(const float4*)(biasa + n);
;       float4 bb = isA ? bba : bbw;
;       float r0 = sigmoid_f(v[0] + bb.x), r1 = sigmoid_f(v[1] + bb.y), r2 = sigmoid_f(v[2] + bb.z), r3 = sigmoid_f(v[3] + bb.w);
;       if (!isA) { r0 = __expf(-DECAY_SCALE * r0); r1 = __expf(-DECAY_SCALE * r1); r2 = __expf(-DECAY_SCALE * r2); r3 = __expf(-DECAY_SCALE * r3); }
;       h16x4 o4 = {(h16)r0, (h16)r1, (h16)r2, (h16)r3};
;       *(h16x4*)(dst + (size_t)(row0 + m) * 1024 + n) = o4;
;     });
.LBB0_360:
	s_nop 0
	v_cvt_pk_f16_f32 v95, v94, v95
	v_cvt_pk_f16_f32 v94, v92, v93
	v_lshl_add_u64 v[92:93], v[110:111], 1, v[98:99]
	global_store_dwordx2 v[92:93], v[94:95], off
	s_and_b64 vcc, exec, s[40:41]
	v_add_f32_e32 v88, v88, v192
	v_add_f32_e32 v89, v89, v193
	v_add_f32_e32 v90, v90, v194
	v_add_f32_e32 v91, v91, v195
	v_mul_f32_e32 v88, 0xbfb8aa3b, v88
	v_mul_f32_e32 v89, 0xbfb8aa3b, v89
	v_mul_f32_e32 v90, 0xbfb8aa3b, v90
	v_mul_f32_e32 v91, 0xbfb8aa3b, v91
	v_exp_f32_e32 v88, v88
	v_exp_f32_e32 v89, v89
	v_exp_f32_e32 v90, v90
	v_exp_f32_e32 v91, v91
	v_add_f32_e32 v88, 1.0, v88
	v_add_f32_e32 v89, 1.0, v89
	v_add_f32_e32 v90, 1.0, v90
	v_add_f32_e32 v91, 1.0, v91
	v_rcp_f32_e32 v88, v88
	v_rcp_f32_e32 v89, v89
	v_rcp_f32_e32 v90, v90
	v_rcp_f32_e32 v91, v91
	s_cbranch_vccnz .LBB0_362
	v_mul_f32_e32 v88, 0xbf1b459e, v88
	v_mul_f32_e32 v89, 0xbf1b459e, v89
	v_mul_f32_e32 v90, 0xbf1b459e, v90
	v_mul_f32_e32 v91, 0xbf1b459e, v91
	v_mul_f32_e32 v88, 0x3fb8aa3b, v88
	v_mul_f32_e32 v89, 0x3fb8aa3b, v89
	v_mul_f32_e32 v90, 0x3fb8aa3b, v90
	v_mul_f32_e32 v91, 0x3fb8aa3b, v91
	v_exp_f32_e32 v88, v88
	v_exp_f32_e32 v89, v89
	v_exp_f32_e32 v90, v90
	v_exp_f32_e32 v91, v91
.LBB0_362:
	s_nop 0
	v_cvt_pk_f16_f32 v91, v90, v91
	v_cvt_pk_f16_f32 v90, v88, v89
	global_store_dwordx2 v[92:93], v[90:91], off offset:32
	s_and_b64 vcc, exec, s[40:41]
	v_add_f32_e32 v84, v84, v196
	v_add_f32_e32 v85, v85, v197
	v_add_f32_e32 v86, v86, v198
	v_add_f32_e32 v87, v87, v199
	v_mul_f32_e32 v84, 0xbfb8aa3b, v84
	v_mul_f32_e32 v85, 0xbfb8aa3b, v85
	v_mul_f32_e32 v86, 0xbfb8aa3b, v86
	v_mul_f32_e32 v87, 0xbfb8aa3b, v87
	v_exp_f32_e32 v84, v84
	v_exp_f32_e32 v85, v85
	v_exp_f32_e32 v86, v86
	v_exp_f32_e32 v87, v87
	v_add_f32_e32 v84, 1.0, v84
	v_add_f32_e32 v85, 1.0, v85
	v_add_f32_e32 v86, 1.0, v86
	v_add_f32_e32 v87, 1.0, v87
	v_rcp_f32_e32 v84, v84
	v_rcp_f32_e32 v85, v85
	v_rcp_f32_e32 v86, v86
	v_rcp_f32_e32 v87, v87
	s_cbranch_vccnz .LBB0_364
	v_mul_f32_e32 v84, 0xbf1b459e, v84
	v_mul_f32_e32 v85, 0xbf1b459e, v85
	v_mul_f32_e32 v86, 0xbf1b459e, v86
	v_mul_f32_e32 v87, 0xbf1b459e, v87
	v_mul_f32_e32 v84, 0x3fb8aa3b, v84
	v_mul_f32_e32 v85, 0x3fb8aa3b, v85
	v_mul_f32_e32 v86, 0x3fb8aa3b, v86
	v_mul_f32_e32 v87, 0x3fb8aa3b, v87
	v_exp_f32_e32 v84, v84
	v_exp_f32_e32 v85, v85
	v_exp_f32_e32 v86, v86
	v_exp_f32_e32 v87, v87
.LBB0_364:
	s_nop 0
	v_cvt_pk_f16_f32 v87, v86, v87
	v_cvt_pk_f16_f32 v86, v84, v85
	global_store_dwordx2 v[92:93], v[86:87], off offset:64
	s_and_b64 vcc, exec, s[40:41]
	v_add_f32_e32 v80, v80, v200
	v_add_f32_e32 v81, v81, v201
	v_add_f32_e32 v82, v82, v202
	v_add_f32_e32 v83, v83, v203
	v_mul_f32_e32 v80, 0xbfb8aa3b, v80
	v_mul_f32_e32 v81, 0xbfb8aa3b, v81
	v_mul_f32_e32 v82, 0xbfb8aa3b, v82
	v_mul_f32_e32 v83, 0xbfb8aa3b, v83
	v_exp_f32_e32 v80, v80
	v_exp_f32_e32 v81, v81
	v_exp_f32_e32 v82, v82
	v_exp_f32_e32 v83, v83
	v_add_f32_e32 v80, 1.0, v80
	v_add_f32_e32 v81, 1.0, v81
	v_add_f32_e32 v82, 1.0, v82
	v_add_f32_e32 v83, 1.0, v83
	v_rcp_f32_e32 v80, v80
	v_rcp_f32_e32 v81, v81
	v_rcp_f32_e32 v82, v82
	v_rcp_f32_e32 v83, v83
	s_cbranch_vccnz .LBB0_366
	v_mul_f32_e32 v80, 0xbf1b459e, v80
	v_mul_f32_e32 v81, 0xbf1b459e, v81
	v_mul_f32_e32 v82, 0xbf1b459e, v82
	v_mul_f32_e32 v83, 0xbf1b459e, v83
	v_mul_f32_e32 v80, 0x3fb8aa3b, v80
	v_mul_f32_e32 v81, 0x3fb8aa3b, v81
	v_mul_f32_e32 v82, 0x3fb8aa3b, v82
	v_mul_f32_e32 v83, 0x3fb8aa3b, v83
	v_exp_f32_e32 v80, v80
	v_exp_f32_e32 v81, v81
	v_exp_f32_e32 v82, v82
	v_exp_f32_e32 v83, v83
.LBB0_366:
	s_nop 0
	v_cvt_pk_f16_f32 v83, v82, v83
	v_cvt_pk_f16_f32 v82, v80, v81
	global_store_dwordx2 v[92:93], v[82:83], off offset:96
	s_and_b64 vcc, exec, s[40:41]
	v_add_f32_e32 v76, v76, v188
	v_add_f32_e32 v77, v77, v189
	v_add_f32_e32 v78, v78, v190
	v_add_f32_e32 v79, v79, v191
	v_mul_f32_e32 v76, 0xbfb8aa3b, v76
	v_mul_f32_e32 v77, 0xbfb8aa3b, v77
	v_mul_f32_e32 v78, 0xbfb8aa3b, v78
	v_mul_f32_e32 v79, 0xbfb8aa3b, v79
	v_exp_f32_e32 v76, v76
	v_exp_f32_e32 v77, v77
	v_exp_f32_e32 v78, v78
	v_exp_f32_e32 v79, v79
	v_add_f32_e32 v76, 1.0, v76
	v_add_f32_e32 v77, 1.0, v77
	v_add_f32_e32 v78, 1.0, v78
	v_add_f32_e32 v79, 1.0, v79
	v_rcp_f32_e32 v76, v76
	v_rcp_f32_e32 v77, v77
	v_rcp_f32_e32 v78, v78
	v_rcp_f32_e32 v79, v79
	s_cbranch_vccnz .LBB0_368
	v_mul_f32_e32 v76, 0xbf1b459e, v76
	v_mul_f32_e32 v77, 0xbf1b459e, v77
	v_mul_f32_e32 v78, 0xbf1b459e, v78
	v_mul_f32_e32 v79, 0xbf1b459e, v79
	v_mul_f32_e32 v76, 0x3fb8aa3b, v76
	v_mul_f32_e32 v77, 0x3fb8aa3b, v77
	v_mul_f32_e32 v78, 0x3fb8aa3b, v78
	v_mul_f32_e32 v79, 0x3fb8aa3b, v79
	v_exp_f32_e32 v76, v76
	v_exp_f32_e32 v77, v77
	v_exp_f32_e32 v78, v78
	v_exp_f32_e32 v79, v79
.LBB0_368:
	s_nop 0
	v_cvt_pk_f16_f32 v79, v78, v79
	v_cvt_pk_f16_f32 v78, v76, v77
	v_lshl_add_u64 v[76:77], v[110:111], 1, v[100:101]
	global_store_dwordx2 v[76:77], v[78:79], off
	s_and_b64 vcc, exec, s[40:41]
	v_add_f32_e32 v72, v72, v192
	v_add_f32_e32 v73, v73, v193
	v_add_f32_e32 v74, v74, v194
	v_add_f32_e32 v75, v75, v195
	v_mul_f32_e32 v72, 0xbfb8aa3b, v72
	v_mul_f32_e32 v73, 0xbfb8aa3b, v73
	v_mul_f32_e32 v74, 0xbfb8aa3b, v74
	v_mul_f32_e32 v75, 0xbfb8aa3b, v75
	v_exp_f32_e32 v72, v72
	v_exp_f32_e32 v73, v73
	v_exp_f32_e32 v74, v74
	v_exp_f32_e32 v75, v75
	v_add_f32_e32 v72, 1.0, v72
	v_add_f32_e32 v73, 1.0, v73
	v_add_f32_e32 v74, 1.0, v74
	v_add_f32_e32 v75, 1.0, v75
	v_rcp_f32_e32 v72, v72
	v_rcp_f32_e32 v73, v73
	v_rcp_f32_e32 v74, v74
	v_rcp_f32_e32 v75, v75
	s_cbranch_vccnz .LBB0_370
	v_mul_f32_e32 v72, 0xbf1b459e, v72
	v_mul_f32_e32 v73, 0xbf1b459e, v73
	v_mul_f32_e32 v74, 0xbf1b459e, v74
	v_mul_f32_e32 v75, 0xbf1b459e, v75
	v_mul_f32_e32 v72, 0x3fb8aa3b, v72
	v_mul_f32_e32 v73, 0x3fb8aa3b, v73
	v_mul_f32_e32 v74, 0x3fb8aa3b, v74
	v_mul_f32_e32 v75, 0x3fb8aa3b, v75
	v_exp_f32_e32 v72, v72
	v_exp_f32_e32 v73, v73
	v_exp_f32_e32 v74, v74
	v_exp_f32_e32 v75, v75
; DEV float sigmoid_f(float x) { return rcp_f(1.f + __expf(-x)); }
; DEV void prep_item(const Params& p, const Ctx& cx, int l, int item, char* smem) {
;     ...
;     for (int hf = 0; hf < 2; ++hf) small_gemm<64, 4>(p, cx, smem, 144, Bt, (tid >> 6) * 128 + hf * 64, [&](int m, int n, f32x4 v) {
;       float4 bbw = *(const float4*)(biasw + n), bba = *(const float4*)(biasa + n);
;       float4 bb = isA ? bba : bbw;
;       float r0 = sigmoid_f(v[0] + bb.x), r1 = sigmoid_f(v[1] + bb.y), r2 = sigmoid_f(v[2] + bb.z), r3 = sigmoid_f(v[3] + bb.w);
;       if (!isA) { r0 = __expf(-DECAY_SCALE * r0); r1 = __expf(-DECAY_SCALE * r1); r2 = __expf(-DECAY_SCALE * r2); r3 = __expf(-DECAY_SCALE * r3); }
;       h16x4 o4 = {(h16)r0, (h16)r1, (h16)r2, (h16)r3};
;       *(h16x4*)(dst + (size_t)(row0 + m) * 1024 + n) = o4;
;     });
.LBB0_370:
	s_nop 0
	v_cvt_pk_f16_f32 v75, v74, v75
	v_cvt_pk_f16_f32 v74, v72, v73
	global_store_dwordx2 v[76:77], v[74:75], off offset:32
	s_and_b64 vcc, exec, s[40:41]
	v_add_f32_e32 v68, v68, v196
	v_add_f32_e32 v69, v69, v197
	v_add_f32_e32 v70, v70, v198
	v_add_f32_e32 v71, v71, v199
	v_mul_f32_e32 v68, 0xbfb8aa3b, v68
	v_mul_f32_e32 v69, 0xbfb8aa3b, v69
	v_mul_f32_e32 v70, 0xbfb8aa3b, v70
	v_mul_f32_e32 v71, 0xbfb8aa3b, v71
	v_exp_f32_e32 v68, v68
	v_exp_f32_e32 v69, v69
	v_exp_f32_e32 v70, v70
	v_exp_f32_e32 v71, v71
	v_add_f32_e32 v68, 1.0, v68
	v_add_f32_e32 v69, 1.0, v69
	v_add_f32_e32 v70, 1.0, v70
	v_add_f32_e32 v71, 1.0, v71
	v_rcp_f32_e32 v68, v68
	v_rcp_f32_e32 v69, v69
	v_rcp_f32_e32 v70, v70
	v_rcp_f32_e32 v71, v71
	s_cbranch_vccnz .LBB0_372
	v_mul_f32_e32 v68, 0xbf1b459e, v68
	v_mul_f32_e32 v69, 0xbf1b459e, v69
	v_mul_f32_e32 v70, 0xbf1b459e, v70
	v_mul_f32_e32 v71, 0xbf1b459e, v71
	v_mul_f32_e32 v68, 0x3fb8aa3b, v68
	v_mul_f32_e32 v69, 0x3fb8aa3b, v69
	v_mul_f32_e32 v70, 0x3fb8aa3b, v70
	v_mul_f32_e32 v71, 0x3fb8aa3b, v71
	v_exp_f32_e32 v68, v68
	v_exp_f32_e32 v69, v69
	v_exp_f32_e32 v70, v70
	v_exp_f32_e32 v71, v71
.LBB0_372:
	s_nop 0
	v_cvt_pk_f16_f32 v71, v70, v71
	v_cvt_pk_f16_f32 v70, v68, v69
	global_store_dwordx2 v[76:77], v[70:71], off offset:64
	s_and_b64 vcc, exec, s[40:41]
	v_add_f32_e32 v64, v64, v200
	v_add_f32_e32 v65, v65, v201
	v_add_f32_e32 v66, v66, v202
	v_add_f32_e32 v67, v67, v203
	v_mul_f32_e32 v64, 0xbfb8aa3b, v64
	v_mul_f32_e32 v65, 0xbfb8aa3b, v65
	v_mul_f32_e32 v66, 0xbfb8aa3b, v66
	v_mul_f32_e32 v67, 0xbfb8aa3b, v67
	v_exp_f32_e32 v64, v64
	v_exp_f32_e32 v65, v65
	v_exp_f32_e32 v66, v66
	v_exp_f32_e32 v67, v67
	v_add_f32_e32 v64, 1.0, v64
	v_add_f32_e32 v65, 1.0, v65
	v_add_f32_e32 v66, 1.0, v66
	v_add_f32_e32 v67, 1.0, v67
	v_rcp_f32_e32 v64, v64
	v_rcp_f32_e32 v65, v65
	v_rcp_f32_e32 v66, v66
	v_rcp_f32_e32 v67, v67
	s_cbranch_vccnz .LBB0_374
	v_mul_f32_e32 v64, 0xbf1b459e, v64
	v_mul_f32_e32 v65, 0xbf1b459e, v65
	v_mul_f32_e32 v66, 0xbf1b459e, v66
	v_mul_f32_e32 v67, 0xbf1b459e, v67
	v_mul_f32_e32 v64, 0x3fb8aa3b, v64
	v_mul_f32_e32 v65, 0x3fb8aa3b, v65
	v_mul_f32_e32 v66, 0x3fb8aa3b, v66
	v_mul_f32_e32 v67, 0x3fb8aa3b, v67
	v_exp_f32_e32 v64, v64
	v_exp_f32_e32 v65, v65
	v_exp_f32_e32 v66, v66
	v_exp_f32_e32 v67, v67
.LBB0_374:
	s_nop 0
	v_cvt_pk_f16_f32 v67, v66, v67
	v_cvt_pk_f16_f32 v66, v64, v65
	global_store_dwordx2 v[76:77], v[66:67], off offset:96
	s_and_b64 vcc, exec, s[40:41]
	v_add_f32_e32 v60, v60, v188
	v_add_f32_e32 v61, v61, v189
	v_add_f32_e32 v62, v62, v190
	v_add_f32_e32 v63, v63, v191
	v_mul_f32_e32 v60, 0xbfb8aa3b, v60
	v_mul_f32_e32 v61, 0xbfb8aa3b, v61
	v_mul_f32_e32 v62, 0xbfb8aa3b, v62
	v_mul_f32_e32 v63, 0xbfb8aa3b, v63
	v_exp_f32_e32 v60, v60
	v_exp_f32_e32 v61, v61
	v_exp_f32_e32 v62, v62
	v_exp_f32_e32 v63, v63
	v_add_f32_e32 v60, 1.0, v60
	v_add_f32_e32 v61, 1.0, v61
	v_add_f32_e32 v62, 1.0, v62
	v_add_f32_e32 v63, 1.0, v63
	v_rcp_f32_e32 v60, v60
	v_rcp_f32_e32 v61, v61
	v_rcp_f32_e32 v62, v62
	v_rcp_f32_e32 v63, v63
	s_cbranch_vccnz .LBB0_376
	v_mul_f32_e32 v60, 0xbf1b459e, v60
	v_mul_f32_e32 v61, 0xbf1b459e, v61
	v_mul_f32_e32 v62, 0xbf1b459e, v62
	v_mul_f32_e32 v63, 0xbf1b459e, v63
	v_mul_f32_e32 v60, 0x3fb8aa3b, v60
	v_mul_f32_e32 v61, 0x3fb8aa3b, v61
	v_mul_f32_e32 v62, 0x3fb8aa3b, v62
	v_mul_f32_e32 v63, 0x3fb8aa3b, v63
	v_exp_f32_e32 v60, v60
	v_exp_f32_e32 v61, v61
	v_exp_f32_e32 v62, v62
	v_exp_f32_e32 v63, v63
.LBB0_376:
	s_nop 0
	v_cvt_pk_f16_f32 v63, v62, v63
	v_cvt_pk_f16_f32 v62, v60, v61
	v_lshl_add_u64 v[60:61], v[110:111], 1, v[102:103]
	global_store_dwordx2 v[60:61], v[62:63], off
	s_and_b64 vcc, exec, s[40:41]
	v_add_f32_e32 v56, v56, v192
	v_add_f32_e32 v57, v57, v193
	v_add_f32_e32 v58, v58, v194
	v_add_f32_e32 v59, v59, v195
	v_mul_f32_e32 v56, 0xbfb8aa3b, v56
	v_mul_f32_e32 v57, 0xbfb8aa3b, v57
	v_mul_f32_e32 v58, 0xbfb8aa3b, v58
	v_mul_f32_e32 v59, 0xbfb8aa3b, v59
	v_exp_f32_e32 v56, v56
	v_exp_f32_e32 v57, v57
	v_exp_f32_e32 v58, v58
	v_exp_f32_e32 v59, v59
	v_add_f32_e32 v56, 1.0, v56
	v_add_f32_e32 v57, 1.0, v57
	v_add_f32_e32 v58, 1.0, v58
	v_add_f32_e32 v59, 1.0, v59
	v_rcp_f32_e32 v56, v56
	v_rcp_f32_e32 v57, v57
	v_rcp_f32_e32 v58, v58
	v_rcp_f32_e32 v59, v59
	s_cbranch_vccnz .LBB0_378
	v_mul_f32_e32 v56, 0xbf1b459e, v56
	v_mul_f32_e32 v57, 0xbf1b459e, v57
	v_mul_f32_e32 v58, 0xbf1b459e, v58
	v_mul_f32_e32 v59, 0xbf1b459e, v59
	v_mul_f32_e32 v56, 0x3fb8aa3b, v56
	v_mul_f32_e32 v57, 0x3fb8aa3b, v57
	v_mul_f32_e32 v58, 0x3fb8aa3b, v58
	v_mul_f32_e32 v59, 0x3fb8aa3b, v59
	v_exp_f32_e32 v56, v56
	v_exp_f32_e32 v57, v57
	v_exp_f32_e32 v58, v58
	v_exp_f32_e32 v59, v59
.LBB0_378:
	s_nop 0
	v_cvt_pk_f16_f32 v59, v58, v59
	v_cvt_pk_f16_f32 v58, v56, v57
	global_store_dwordx2 v[60:61], v[58:59], off offset:32
	s_and_b64 vcc, exec, s[40:41]
	v_add_f32_e32 v52, v52, v196
	v_add_f32_e32 v53, v53, v197
	v_add_f32_e32 v54, v54, v198
	v_add_f32_e32 v55, v55, v199
	v_mul_f32_e32 v52, 0xbfb8aa3b, v52
	v_mul_f32_e32 v53, 0xbfb8aa3b, v53
	v_mul_f32_e32 v54, 0xbfb8aa3b, v54
	v_mul_f32_e32 v55, 0xbfb8aa3b, v55
	v_exp_f32_e32 v52, v52
	v_exp_f32_e32 v53, v53
	v_exp_f32_e32 v54, v54
	v_exp_f32_e32 v55, v55
	v_add_f32_e32 v52, 1.0, v52
	v_add_f32_e32 v53, 1.0, v53
	v_add_f32_e32 v54, 1.0, v54
	v_add_f32_e32 v55, 1.0, v55
	v_rcp_f32_e32 v52, v52
	v_rcp_f32_e32 v53, v53
	v_rcp_f32_e32 v54, v54
	v_rcp_f32_e32 v55, v55
	s_cbranch_vccnz .LBB0_380
	v_mul_f32_e32 v52, 0xbf1b459e, v52
	v_mul_f32_e32 v53, 0xbf1b459e, v53
	v_mul_f32_e32 v54, 0xbf1b459e, v54
	v_mul_f32_e32 v55, 0xbf1b459e, v55
	v_mul_f32_e32 v52, 0x3fb8aa3b, v52
	v_mul_f32_e32 v53, 0x3fb8aa3b, v53
	v_mul_f32_e32 v54, 0x3fb8aa3b, v54
	v_mul_f32_e32 v55, 0x3fb8aa3b, v55
	v_exp_f32_e32 v52, v52
	v_exp_f32_e32 v53, v53
	v_exp_f32_e32 v54, v54
	v_exp_f32_e32 v55, v55
; DEV float sigmoid_f(float x) { return rcp_f(1.f + __expf(-x)); }
; DEV void prep_item(const Params& p, const Ctx& cx, int l, int item, char* smem) {
;     ...
;     for (int hf = 0; hf < 2; ++hf) small_gemm<64, 4>(p, cx, smem, 144, Bt, (tid >> 6) * 128 + hf * 64, [&](int m, int n, f32x4 v) {
;       float4 bbw = *(const float4*)(biasw + n), bba = *(const float4*)(biasa + n);
;       float4 bb = isA ? bba : bbw;
;       float r0 = sigmoid_f(v[0] + bb.x), r1 = sigmoid_f(v[1] + bb.y), r2 = sigmoid_f(v[2] + bb.z), r3 = sigmoid_f(v[3] + bb.w);
;       if (!isA) { r0 = __expf(-DECAY_SCALE * r0); r1 = __expf(-DECAY_SCALE * r1); r2 = __expf(-DECAY_SCALE * r2); r3 = __expf(-DECAY_SCALE * r3); }
;       h16x4 o4 = {(h16)r0, (h16)r1, (h16)r2, (h16)r3};
;       *(h16x4*)(dst + (size_t)(row0 + m) * 1024 + n) = o4;
;     });
.LBB0_380:
	s_nop 0
	v_cvt_pk_f16_f32 v55, v54, v55
	v_cvt_pk_f16_f32 v54, v52, v53
	global_store_dwordx2 v[60:61], v[54:55], off offset:64
	s_and_b64 vcc, exec, s[40:41]
	v_add_f32_e32 v48, v48, v200
	v_add_f32_e32 v49, v49, v201
	v_add_f32_e32 v50, v50, v202
	v_add_f32_e32 v51, v51, v203
	v_mul_f32_e32 v48, 0xbfb8aa3b, v48
	v_mul_f32_e32 v49, 0xbfb8aa3b, v49
	v_mul_f32_e32 v50, 0xbfb8aa3b, v50
	v_mul_f32_e32 v51, 0xbfb8aa3b, v51
	v_exp_f32_e32 v48, v48
	v_exp_f32_e32 v49, v49
	v_exp_f32_e32 v50, v50
	v_exp_f32_e32 v51, v51
	v_add_f32_e32 v48, 1.0, v48
	v_add_f32_e32 v49, 1.0, v49
	v_add_f32_e32 v50, 1.0, v50
	v_add_f32_e32 v51, 1.0, v51
	v_rcp_f32_e32 v48, v48
	v_rcp_f32_e32 v49, v49
	v_rcp_f32_e32 v50, v50
	v_rcp_f32_e32 v51, v51
	s_cbranch_vccnz .LBB0_382
	v_mul_f32_e32 v48, 0xbf1b459e, v48
	v_mul_f32_e32 v49, 0xbf1b459e, v49
	v_mul_f32_e32 v50, 0xbf1b459e, v50
	v_mul_f32_e32 v51, 0xbf1b459e, v51
	v_mul_f32_e32 v48, 0x3fb8aa3b, v48
	v_mul_f32_e32 v49, 0x3fb8aa3b, v49
	v_mul_f32_e32 v50, 0x3fb8aa3b, v50
	v_mul_f32_e32 v51, 0x3fb8aa3b, v51
	v_exp_f32_e32 v48, v48
	v_exp_f32_e32 v49, v49
	v_exp_f32_e32 v50, v50
	v_exp_f32_e32 v51, v51
.LBB0_382:
	s_nop 0
	v_cvt_pk_f16_f32 v51, v50, v51
	v_cvt_pk_f16_f32 v50, v48, v49
	global_store_dwordx2 v[60:61], v[50:51], off offset:96
	s_and_b64 vcc, exec, s[40:41]
	v_add_f32_e32 v44, v44, v188
	v_add_f32_e32 v45, v45, v189
	v_add_f32_e32 v46, v46, v190
	v_add_f32_e32 v47, v47, v191
	v_mul_f32_e32 v44, 0xbfb8aa3b, v44
	v_mul_f32_e32 v45, 0xbfb8aa3b, v45
	v_mul_f32_e32 v46, 0xbfb8aa3b, v46
	v_mul_f32_e32 v47, 0xbfb8aa3b, v47
	v_exp_f32_e32 v44, v44
	v_exp_f32_e32 v45, v45
	v_exp_f32_e32 v46, v46
	v_exp_f32_e32 v47, v47
	v_add_f32_e32 v44, 1.0, v44
	v_add_f32_e32 v45, 1.0, v45
	v_add_f32_e32 v46, 1.0, v46
	v_add_f32_e32 v47, 1.0, v47
	v_rcp_f32_e32 v44, v44
	v_rcp_f32_e32 v45, v45
	v_rcp_f32_e32 v46, v46
	v_rcp_f32_e32 v47, v47
	s_cbranch_vccnz .LBB0_384
	v_mul_f32_e32 v44, 0xbf1b459e, v44
	v_mul_f32_e32 v45, 0xbf1b459e, v45
	v_mul_f32_e32 v46, 0xbf1b459e, v46
	v_mul_f32_e32 v47, 0xbf1b459e, v47
	v_mul_f32_e32 v44, 0x3fb8aa3b, v44
	v_mul_f32_e32 v45, 0x3fb8aa3b, v45
	v_mul_f32_e32 v46, 0x3fb8aa3b, v46
	v_mul_f32_e32 v47, 0x3fb8aa3b, v47
	v_exp_f32_e32 v44, v44
	v_exp_f32_e32 v45, v45
	v_exp_f32_e32 v46, v46
	v_exp_f32_e32 v47, v47
.LBB0_384:
	s_nop 0
	v_cvt_pk_f16_f32 v47, v46, v47
	v_cvt_pk_f16_f32 v46, v44, v45
	v_lshl_add_u64 v[44:45], v[110:111], 1, v[104:105]
	global_store_dwordx2 v[44:45], v[46:47], off
	s_and_b64 vcc, exec, s[40:41]
	v_add_f32_e32 v40, v40, v192
	v_add_f32_e32 v41, v41, v193
	v_add_f32_e32 v42, v42, v194
	v_add_f32_e32 v43, v43, v195
	v_mul_f32_e32 v40, 0xbfb8aa3b, v40
	v_mul_f32_e32 v41, 0xbfb8aa3b, v41
	v_mul_f32_e32 v42, 0xbfb8aa3b, v42
	v_mul_f32_e32 v43, 0xbfb8aa3b, v43
	v_exp_f32_e32 v40, v40
	v_exp_f32_e32 v41, v41
	v_exp_f32_e32 v42, v42
	v_exp_f32_e32 v43, v43
	v_add_f32_e32 v40, 1.0, v40
	v_add_f32_e32 v41, 1.0, v41
	v_add_f32_e32 v42, 1.0, v42
	v_add_f32_e32 v43, 1.0, v43
	v_rcp_f32_e32 v40, v40
	v_rcp_f32_e32 v41, v41
	v_rcp_f32_e32 v42, v42
	v_rcp_f32_e32 v43, v43
	s_cbranch_vccnz .LBB0_386
	v_mul_f32_e32 v40, 0xbf1b459e, v40
	v_mul_f32_e32 v41, 0xbf1b459e, v41
	v_mul_f32_e32 v42, 0xbf1b459e, v42
	v_mul_f32_e32 v43, 0xbf1b459e, v43
	v_mul_f32_e32 v40, 0x3fb8aa3b, v40
	v_mul_f32_e32 v41, 0x3fb8aa3b, v41
	v_mul_f32_e32 v42, 0x3fb8aa3b, v42
	v_mul_f32_e32 v43, 0x3fb8aa3b, v43
	v_exp_f32_e32 v40, v40
	v_exp_f32_e32 v41, v41
	v_exp_f32_e32 v42, v42
	v_exp_f32_e32 v43, v43
.LBB0_386:
	s_nop 0
	v_cvt_pk_f16_f32 v43, v42, v43
	v_cvt_pk_f16_f32 v42, v40, v41
	global_store_dwordx2 v[44:45], v[42:43], off offset:32
	s_and_b64 vcc, exec, s[40:41]
	v_add_f32_e32 v36, v36, v196
	v_add_f32_e32 v37, v37, v197
	v_add_f32_e32 v38, v38, v198
	v_add_f32_e32 v39, v39, v199
	v_mul_f32_e32 v36, 0xbfb8aa3b, v36
	v_mul_f32_e32 v37, 0xbfb8aa3b, v37
	v_mul_f32_e32 v38, 0xbfb8aa3b, v38
	v_mul_f32_e32 v39, 0xbfb8aa3b, v39
	v_exp_f32_e32 v36, v36
	v_exp_f32_e32 v37, v37
	v_exp_f32_e32 v38, v38
	v_exp_f32_e32 v39, v39
	v_add_f32_e32 v36, 1.0, v36
	v_add_f32_e32 v37, 1.0, v37
	v_add_f32_e32 v38, 1.0, v38
	v_add_f32_e32 v39, 1.0, v39
	v_rcp_f32_e32 v36, v36
	v_rcp_f32_e32 v37, v37
	v_rcp_f32_e32 v38, v38
	v_rcp_f32_e32 v39, v39
	s_cbranch_vccnz .LBB0_388
	v_mul_f32_e32 v36, 0xbf1b459e, v36
	v_mul_f32_e32 v37, 0xbf1b459e, v37
	v_mul_f32_e32 v38, 0xbf1b459e, v38
	v_mul_f32_e32 v39, 0xbf1b459e, v39
	v_mul_f32_e32 v36, 0x3fb8aa3b, v36
	v_mul_f32_e32 v37, 0x3fb8aa3b, v37
	v_mul_f32_e32 v38, 0x3fb8aa3b, v38
	v_mul_f32_e32 v39, 0x3fb8aa3b, v39
	v_exp_f32_e32 v36, v36
	v_exp_f32_e32 v37, v37
	v_exp_f32_e32 v38, v38
	v_exp_f32_e32 v39, v39
.LBB0_388:
	s_nop 0
	v_cvt_pk_f16_f32 v39, v38, v39
	v_cvt_pk_f16_f32 v38, v36, v37
	global_store_dwordx2 v[44:45], v[38:39], off offset:64
	s_and_b64 vcc, exec, s[40:41]
	v_add_f32_e32 v32, v32, v200
	v_add_f32_e32 v33, v33, v201
	v_add_f32_e32 v34, v34, v202
	v_add_f32_e32 v35, v35, v203
	v_mul_f32_e32 v32, 0xbfb8aa3b, v32
	v_mul_f32_e32 v33, 0xbfb8aa3b, v33
	v_mul_f32_e32 v34, 0xbfb8aa3b, v34
	v_mul_f32_e32 v35, 0xbfb8aa3b, v35
	v_exp_f32_e32 v32, v32
	v_exp_f32_e32 v33, v33
	v_exp_f32_e32 v34, v34
	v_exp_f32_e32 v35, v35
	v_add_f32_e32 v32, 1.0, v32
	v_add_f32_e32 v33, 1.0, v33
	v_add_f32_e32 v34, 1.0, v34
	v_add_f32_e32 v35, 1.0, v35
	v_rcp_f32_e32 v32, v32
	v_rcp_f32_e32 v33, v33
	v_rcp_f32_e32 v34, v34
	v_rcp_f32_e32 v35, v35
	s_cbranch_vccnz .LBB0_357
	v_mul_f32_e32 v32, 0xbf1b459e, v32
	v_mul_f32_e32 v33, 0xbf1b459e, v33
	v_mul_f32_e32 v34, 0xbf1b459e, v34
	v_mul_f32_e32 v35, 0xbf1b459e, v35
	v_mul_f32_e32 v32, 0x3fb8aa3b, v32
	v_mul_f32_e32 v33, 0x3fb8aa3b, v33
	v_mul_f32_e32 v34, 0x3fb8aa3b, v34
	v_mul_f32_e32 v35, 0x3fb8aa3b, v35
	v_exp_f32_e32 v32, v32
	v_exp_f32_e32 v33, v33
	v_exp_f32_e32 v34, v34
	v_exp_f32_e32 v35, v35
	s_branch .LBB0_357
